# grid barrier / handoff spin bounds raised from 0x800 to 0x2000 polls (robustness only)
# speedup vs baseline: 1.0088x; 1.0049x over previous
; #define RUN_PHASE(k, fn)                                  \
;   if (ph_lo <= k && k <= ph_hi) {                         \
;     if (k == PROBE_DUP) { fn(p, smem); cg::this_grid().sync(); } \
;     fn(p, smem);                                          \
;     if (k < ph_hi) cg::this_grid().sync();                \
;   }
; __global__ void __launch_bounds__(512) mega(Params p, int ph_lo, int ph_hi) {
;     ...
;   RUN_PHASE(0, phase0)
.Lgbf_rdy_init:
	s_movk_i32 s11, 0x2000

; #define RUN_PHASE(k, fn)                                  \
;   if (ph_lo <= k && k <= ph_hi) {                         \
;     if (k == PROBE_DUP) { fn(p, smem); cg::this_grid().sync(); } \
;     fn(p, smem);                                          \
;     if (k < ph_hi) cg::this_grid().sync();                \
;   }
; __global__ void __launch_bounds__(512) mega(Params p, int ph_lo, int ph_hi) {
;     ...
;   RUN_PHASE(0, phase0)
.Lgbf_rdy_ok:
	s_lshl_b32 s0, s100, 8
	v_mov_b32_e32 v1, s0
	global_atomic_add v1, v11, s[86:87]
	s_movk_i32 s11, 0x2000

; #define RUN_PHASE(k, fn)                                  \
;   if (ph_lo <= k && k <= ph_hi) {                         \
;     if (k == PROBE_DUP) { fn(p, smem); cg::this_grid().sync(); } \
;     fn(p, smem);                                          \
;     if (k < ph_hi) cg::this_grid().sync();                \
;   }
; __global__ void __launch_bounds__(512) mega(Params p, int ph_lo, int ph_hi) {
;     ...
;   RUN_PHASE(0, phase0)
.Lgbf_wait:
	v_mov_b32_e32 v1, s2
	s_movk_i32 s11, 0x2000

; #define PG8_STAGE(bufoff, gbase, voff) do { _Pragma("unroll") for (int _i = 0; _i < 2; ++_i) \
;         __builtin_amdgcn_global_load_lds((const unsigned*)((const char*)(gbase) + (voff)[_i]), (PG8_LAS unsigned*)(lds + (bufoff) + ldsw + _i * 8192), 16, 0, 0); } while (0)
; #define PG8_LDA(dst, b, h) do { _Pragma("unroll") for (int m = 0; m < 4; ++m) _Pragma("unroll") for (int k = 0; k < 2; ++k) dst[m][k] = *(const PG8_LAS bf16x8*)(lds + PG8_SA(b, h) + aoff + m * 2048 + k * 1024); } while (0)
; #define PG8_LDB(dst, b, h) do { _Pragma("unroll") for (int n = 0; n < 2; ++n) _Pragma("unroll") for (int k = 0; k < 2; ++k) dst[n][k] = *(const PG8_LAS bf16x8*)(lds + PG8_SB(b, h) + boff + n * 2048 + k * 1024); } while (0)
; #define PG8_MMA(ai, bj, At, Bt) do { __builtin_amdgcn_s_setprio(1); _Pragma("unroll") for (int m = 0; m < 4; ++m) _Pragma("unroll") for (int n = 0; n < 2; ++n) _Pragma("unroll") for (int k = 0; k < 2; ++k) \
;         acc[ai][bj][m][n] = __builtin_amdgcn_mfma_f32_16x16x32_bf16(Bt[n][k], At[m][k], acc[ai][bj][m][n], 0, 0, 0); __builtin_amdgcn_s_setprio(0); } while (0)
; #define PG8_WAIT_V(n) asm volatile("s_waitcnt vmcnt(" #n ")" ::: "memory")
; #define PG8_WAIT_L(n) asm volatile("s_waitcnt lgkmcnt(" #n ")" ::: "memory")
; template <class Epi, class Sched>
; __device__ __forceinline__ void gemm_phase(PG8_LAS unsigned char* lds, const Gemm g, const Sched& S, const Epi& E) {
;     ...
;         for (int t = 0; t < nt; t += 2) {
;             const bool last = (t == nt - 2);
;             const char* a1 = cA + (size_t)(t + 1) * kstep;
;             const char* a2 = last ? nA : cA + (size_t)(t + 2) * kstep; const char* b2 = last ? nB : cB + (size_t)(t + 2) * kstep;
;             const char* a3 = a2 + kstep; const char* b3 = b2 + kstep;
;             PG8_LDB(B0, 0, 0); PG8_SCHED; PG8_LDA(At, 0, 0); PG8_STAGE(PG8_SA(1, 1), a1 + hstep, voffA);
;             PG8_WAIT_L(8); PG8_BAR; PG8_WAIT_L(0); PG8_MMA(0, 0, At, B0); PG8_BAR; PG8_SCHED;
;             PG8_LDB(B1, 0, 1); PG8_STAGE(PG8_SB(0, 0), b2, voffB);
;             PG8_BAR; PG8_WAIT_L(0); PG8_MMA(0, 1, At, B1); PG8_BAR;
;             PG8_LDA(At, 0, 1); PG8_STAGE(PG8_SA(0, 0), a2, voffA);
;             PG8_BAR; PG8_WAIT_L(0); PG8_MMA(1, 0, At, B0); PG8_BAR; PG8_SCHED;
;             PG8_STAGE(PG8_SB(0, 1), b2 + hstep, voffB);
;             PG8_WAIT_V(6); PG8_BAR; PG8_MMA(1, 1, At, B1); PG8_BAR;
.LBB0_713:
	ds_read_b128 v[138:141], v157
	ds_read_b128 v[142:145], v158
	ds_read_b128 v[146:149], v159
	ds_read_b128 v[150:153], v160
	s_add_u32 s28, s26, 0xfffe0080
	s_addc_u32 s29, s27, -1
	s_cmp_eq_u32 s61, 4
	s_cselect_b32 s31, s15, s29
	s_cselect_b32 s30, s57, s28
	s_cselect_b32 s29, s13, s60
	s_cselect_b32 s28, s58, s59
	s_mov_b32 m0, s51
	v_lshl_add_u64 v[206:207], s[26:27], 0, v[134:135]
	ds_read_b128 v[174:177], v155
	ds_read_b128 v[178:181], v155 offset:1024
	ds_read_b128 v[182:185], v155 offset:2048
	ds_read_b128 v[186:189], v155 offset:3072
	ds_read_b128 v[190:193], v155 offset:4096
	ds_read_b128 v[194:197], v155 offset:5120
	ds_read_b128 v[198:201], v155 offset:6144
	ds_read_b128 v[202:205], v155 offset:7168
	global_load_lds_dwordx4 v[206:207], off
	v_lshl_add_u64 v[206:207], s[26:27], 0, v[136:137]
	s_mov_b32 m0, s56
	s_nop 0
	global_load_lds_dwordx4 v[206:207], off
	s_waitcnt lgkmcnt(8)
	s_barrier
	s_waitcnt lgkmcnt(0)
	s_setprio 1
	s_waitcnt lgkmcnt(0)
	v_mfma_f32_16x16x32_bf16 v[126:129], v[138:141], v[174:177], v[126:129]
	v_mfma_f32_16x16x32_bf16 v[122:125], v[146:149], v[174:177], v[122:125]
	v_mfma_f32_16x16x32_bf16 v[110:113], v[138:141], v[182:185], v[110:113]
	v_mfma_f32_16x16x32_bf16 v[106:109], v[146:149], v[182:185], v[106:109]
	v_mfma_f32_16x16x32_bf16 v[98:101], v[138:141], v[190:193], v[98:101]
	v_mfma_f32_16x16x32_bf16 v[90:93], v[146:149], v[190:193], v[90:93]
	v_mfma_f32_16x16x32_bf16 v[86:89], v[138:141], v[198:201], v[86:89]
	v_mfma_f32_16x16x32_bf16 v[82:85], v[146:149], v[198:201], v[82:85]
	v_mfma_f32_16x16x32_bf16 v[126:129], v[142:145], v[178:181], v[126:129]
	v_mfma_f32_16x16x32_bf16 v[122:125], v[150:153], v[178:181], v[122:125]
	v_mfma_f32_16x16x32_bf16 v[110:113], v[142:145], v[186:189], v[110:113]
	v_mfma_f32_16x16x32_bf16 v[106:109], v[150:153], v[186:189], v[106:109]
	v_mfma_f32_16x16x32_bf16 v[98:101], v[142:145], v[194:197], v[98:101]
	v_mfma_f32_16x16x32_bf16 v[90:93], v[150:153], v[194:197], v[90:93]
	v_mfma_f32_16x16x32_bf16 v[86:89], v[142:145], v[202:205], v[86:89]
	v_mfma_f32_16x16x32_bf16 v[82:85], v[150:153], v[202:205], v[82:85]
	s_setprio 0
	s_barrier
	s_mov_b32 m0, s23
	v_lshl_add_u64 v[222:223], s[28:29], 0, v[130:131]
	ds_read_b128 v[206:209], v161
	ds_read_b128 v[210:213], v162
	ds_read_b128 v[214:217], v163
	ds_read_b128 v[218:221], v164
	global_load_lds_dwordx4 v[222:223], off
	v_lshl_add_u64 v[224:225], s[28:29], 0, v[132:133]
	s_mov_b32 m0, s25
	s_nop 0
	global_load_lds_dwordx4 v[224:225], off
	s_barrier
	s_waitcnt lgkmcnt(0)
	s_setprio 1
	s_waitcnt lgkmcnt(0)
	v_mfma_f32_16x16x32_bf16 v[118:121], v[206:209], v[174:177], v[118:121]
	v_mfma_f32_16x16x32_bf16 v[114:117], v[214:217], v[174:177], v[114:117]
	v_mfma_f32_16x16x32_bf16 v[102:105], v[206:209], v[182:185], v[102:105]
	v_mfma_f32_16x16x32_bf16 v[94:97], v[214:217], v[182:185], v[94:97]
	v_mfma_f32_16x16x32_bf16 v[78:81], v[206:209], v[190:193], v[78:81]
	v_mfma_f32_16x16x32_bf16 v[74:77], v[214:217], v[190:193], v[74:77]
	v_mfma_f32_16x16x32_bf16 v[70:73], v[206:209], v[198:201], v[70:73]
	v_mfma_f32_16x16x32_bf16 v[66:69], v[214:217], v[198:201], v[66:69]
	v_mfma_f32_16x16x32_bf16 v[118:121], v[210:213], v[178:181], v[118:121]
	v_mfma_f32_16x16x32_bf16 v[114:117], v[218:221], v[178:181], v[114:117]
	v_mfma_f32_16x16x32_bf16 v[102:105], v[210:213], v[186:189], v[102:105]
	v_mfma_f32_16x16x32_bf16 v[94:97], v[218:221], v[186:189], v[94:97]
	v_mfma_f32_16x16x32_bf16 v[78:81], v[210:213], v[194:197], v[78:81]
	v_mfma_f32_16x16x32_bf16 v[74:77], v[218:221], v[194:197], v[74:77]
	v_mfma_f32_16x16x32_bf16 v[70:73], v[210:213], v[202:205], v[70:73]
	v_mfma_f32_16x16x32_bf16 v[66:69], v[218:221], v[202:205], v[66:69]
	s_setprio 0
	s_mov_b32 m0, s38
	v_lshl_add_u64 v[226:227], s[30:31], 0, v[130:131]
	s_barrier
	ds_read_b128 v[174:177], v155 offset:16384
	ds_read_b128 v[178:181], v155 offset:17408
	ds_read_b128 v[182:185], v155 offset:18432
	ds_read_b128 v[186:189], v155 offset:19456
	ds_read_b128 v[190:193], v155 offset:20480
	ds_read_b128 v[194:197], v155 offset:21504
	ds_read_b128 v[198:201], v155 offset:22528
	ds_read_b128 v[202:205], v155 offset:23552
	global_load_lds_dwordx4 v[226:227], off
	v_lshl_add_u64 v[228:229], s[30:31], 0, v[132:133]
	s_mov_b32 m0, s39
	s_nop 0
	global_load_lds_dwordx4 v[228:229], off
	s_barrier
	s_waitcnt lgkmcnt(0)
	s_setprio 1
	s_waitcnt lgkmcnt(0)
	v_mfma_f32_16x16x32_bf16 v[62:65], v[138:141], v[174:177], v[62:65]
	v_mfma_f32_16x16x32_bf16 v[58:61], v[146:149], v[174:177], v[58:61]
	v_mfma_f32_16x16x32_bf16 v[46:49], v[138:141], v[182:185], v[46:49]
	v_mfma_f32_16x16x32_bf16 v[42:45], v[146:149], v[182:185], v[42:45]
	v_mfma_f32_16x16x32_bf16 v[30:33], v[138:141], v[190:193], v[30:33]
	v_mfma_f32_16x16x32_bf16 v[26:29], v[146:149], v[190:193], v[26:29]
	v_mfma_f32_16x16x32_bf16 v[14:17], v[138:141], v[198:201], v[14:17]
	v_mfma_f32_16x16x32_bf16 v[10:13], v[146:149], v[198:201], v[10:13]
	v_mfma_f32_16x16x32_bf16 v[62:65], v[142:145], v[178:181], v[62:65]
	v_mfma_f32_16x16x32_bf16 v[58:61], v[150:153], v[178:181], v[58:61]
	v_mfma_f32_16x16x32_bf16 v[46:49], v[142:145], v[186:189], v[46:49]
	v_mfma_f32_16x16x32_bf16 v[42:45], v[150:153], v[186:189], v[42:45]
	v_mfma_f32_16x16x32_bf16 v[30:33], v[142:145], v[194:197], v[30:33]
	v_mfma_f32_16x16x32_bf16 v[26:29], v[150:153], v[194:197], v[26:29]
	v_mfma_f32_16x16x32_bf16 v[14:17], v[142:145], v[202:205], v[14:17]
	v_mfma_f32_16x16x32_bf16 v[10:13], v[150:153], v[202:205], v[10:13]
	s_setprio 0
	s_barrier
; #define PG8_STAGE(bufoff, gbase, voff) do { _Pragma("unroll") for (int _i = 0; _i < 2; ++_i) \
;         __builtin_amdgcn_global_load_lds((const unsigned*)((const char*)(gbase) + (voff)[_i]), (PG8_LAS unsigned*)(lds + (bufoff) + ldsw + _i * 8192), 16, 0, 0); } while (0)
; #define PG8_LDA(dst, b, h) do { _Pragma("unroll") for (int m = 0; m < 4; ++m) _Pragma("unroll") for (int k = 0; k < 2; ++k) dst[m][k] = *(const PG8_LAS bf16x8*)(lds + PG8_SA(b, h) + aoff + m * 2048 + k * 1024); } while (0)
; #define PG8_LDB(dst, b, h) do { _Pragma("unroll") for (int n = 0; n < 2; ++n) _Pragma("unroll") for (int k = 0; k < 2; ++k) dst[n][k] = *(const PG8_LAS bf16x8*)(lds + PG8_SB(b, h) + boff + n * 2048 + k * 1024); } while (0)
; #define PG8_MMA(ai, bj, At, Bt) do { __builtin_amdgcn_s_setprio(1); _Pragma("unroll") for (int m = 0; m < 4; ++m) _Pragma("unroll") for (int n = 0; n < 2; ++n) _Pragma("unroll") for (int k = 0; k < 2; ++k) \
;         acc[ai][bj][m][n] = __builtin_amdgcn_mfma_f32_16x16x32_bf16(Bt[n][k], At[m][k], acc[ai][bj][m][n], 0, 0, 0); __builtin_amdgcn_s_setprio(0); } while (0)
; #define PG8_WAIT_V(n) asm volatile("s_waitcnt vmcnt(" #n ")" ::: "memory")
; #define PG8_WAIT_L(n) asm volatile("s_waitcnt lgkmcnt(" #n ")" ::: "memory")
; #define PG8_BAR __builtin_amdgcn_s_barrier()
; #define PG8_SCHED __builtin_amdgcn_sched_barrier(0)
; template <class Epi, class Sched>
; __device__ __forceinline__ void gemm_phase(PG8_LAS unsigned char* lds, const Gemm g, const Sched& S, const Epi& E) {
;     ...
;             PG8_STAGE(PG8_SB(0, 1), b2 + hstep, voffB);
;             PG8_WAIT_V(6); PG8_BAR; PG8_MMA(1, 1, At, B1); PG8_BAR;
;             PG8_LDB(B0, 1, 0); PG8_SCHED; PG8_LDA(At, 1, 0); PG8_STAGE(PG8_SA(0, 1), a2 + hstep, voffA);
;             PG8_WAIT_L(8); PG8_BAR; PG8_WAIT_L(0); PG8_MMA(0, 0, At, B0); PG8_BAR; PG8_SCHED;
;             PG8_LDB(B1, 1, 1); PG8_STAGE(PG8_SB(1, 0), b3, voffB);
;             PG8_BAR; PG8_WAIT_L(0); PG8_MMA(0, 1, At, B1); PG8_BAR;
;             PG8_LDA(At, 1, 1); PG8_STAGE(PG8_SA(1, 0), a3, voffA);
;             PG8_BAR; PG8_WAIT_L(0); PG8_MMA(1, 0, At, B0); PG8_BAR; PG8_SCHED;
;             PG8_STAGE(PG8_SB(1, 1), b3 + hstep, voffB);
;             PG8_WAIT_V(6); PG8_BAR; PG8_MMA(1, 1, At, B1); PG8_BAR;
	s_add_u32 s62, s28, 0x20000
	s_addc_u32 s63, s29, 0
	s_mov_b32 m0, s40
	v_lshl_add_u64 v[138:139], s[62:63], 0, v[130:131]
	global_load_lds_dwordx4 v[138:139], off
	v_lshl_add_u64 v[138:139], s[62:63], 0, v[132:133]
	s_mov_b32 m0, s41
	s_nop 0
	global_load_lds_dwordx4 v[138:139], off
	s_waitcnt vmcnt(6)
	s_barrier
	s_setprio 1
	v_mfma_f32_16x16x32_bf16 v[54:57], v[206:209], v[174:177], v[54:57]
	v_mfma_f32_16x16x32_bf16 v[50:53], v[214:217], v[174:177], v[50:53]
	v_mfma_f32_16x16x32_bf16 v[38:41], v[206:209], v[182:185], v[38:41]
	v_mfma_f32_16x16x32_bf16 v[34:37], v[214:217], v[182:185], v[34:37]
	v_mfma_f32_16x16x32_bf16 v[22:25], v[206:209], v[190:193], v[22:25]
	v_mfma_f32_16x16x32_bf16 v[18:21], v[214:217], v[190:193], v[18:21]
	v_mfma_f32_16x16x32_bf16 v[6:9], v[206:209], v[198:201], v[6:9]
	v_mfma_f32_16x16x32_bf16 v[2:5], v[214:217], v[198:201], v[2:5]
	v_mfma_f32_16x16x32_bf16 v[54:57], v[210:213], v[178:181], v[54:57]
	v_mfma_f32_16x16x32_bf16 v[50:53], v[218:221], v[178:181], v[50:53]
	v_mfma_f32_16x16x32_bf16 v[38:41], v[210:213], v[186:189], v[38:41]
	v_mfma_f32_16x16x32_bf16 v[34:37], v[218:221], v[186:189], v[34:37]
	v_mfma_f32_16x16x32_bf16 v[22:25], v[210:213], v[194:197], v[22:25]
	v_mfma_f32_16x16x32_bf16 v[18:21], v[218:221], v[194:197], v[18:21]
	v_mfma_f32_16x16x32_bf16 v[6:9], v[210:213], v[202:205], v[6:9]
	v_mfma_f32_16x16x32_bf16 v[2:5], v[218:221], v[202:205], v[2:5]
	s_setprio 0
	s_barrier
	ds_read_b128 v[138:141], v165
	ds_read_b128 v[142:145], v166
	ds_read_b128 v[146:149], v167
	ds_read_b128 v[150:153], v168
	s_add_u32 s30, s30, 0x20000
	s_addc_u32 s31, s31, 0
	s_mov_b32 m0, s42
	v_lshl_add_u64 v[206:207], s[30:31], 0, v[130:131]
	ds_read_b128 v[174:177], v155 offset:32768
	ds_read_b128 v[178:181], v155 offset:33792
	ds_read_b128 v[182:185], v155 offset:34816
	ds_read_b128 v[186:189], v155 offset:35840
	ds_read_b128 v[190:193], v155 offset:36864
	ds_read_b128 v[194:197], v155 offset:37888
	ds_read_b128 v[198:201], v155 offset:38912
	ds_read_b128 v[202:205], v155 offset:39936
	global_load_lds_dwordx4 v[206:207], off
	v_lshl_add_u64 v[206:207], s[30:31], 0, v[132:133]
	s_mov_b32 m0, s43
	s_nop 0
	global_load_lds_dwordx4 v[206:207], off
	s_waitcnt lgkmcnt(8)
	s_barrier
	s_waitcnt lgkmcnt(0)
	s_setprio 1
	s_waitcnt lgkmcnt(0)
	v_mfma_f32_16x16x32_bf16 v[126:129], v[138:141], v[174:177], v[126:129]
	v_mfma_f32_16x16x32_bf16 v[122:125], v[146:149], v[174:177], v[122:125]
	v_mfma_f32_16x16x32_bf16 v[110:113], v[138:141], v[182:185], v[110:113]
	v_mfma_f32_16x16x32_bf16 v[106:109], v[146:149], v[182:185], v[106:109]
	v_mfma_f32_16x16x32_bf16 v[98:101], v[138:141], v[190:193], v[98:101]
	v_mfma_f32_16x16x32_bf16 v[90:93], v[146:149], v[190:193], v[90:93]
	v_mfma_f32_16x16x32_bf16 v[86:89], v[138:141], v[198:201], v[86:89]
	v_mfma_f32_16x16x32_bf16 v[82:85], v[146:149], v[198:201], v[82:85]
	v_mfma_f32_16x16x32_bf16 v[126:129], v[142:145], v[178:181], v[126:129]
	v_mfma_f32_16x16x32_bf16 v[122:125], v[150:153], v[178:181], v[122:125]
	v_mfma_f32_16x16x32_bf16 v[110:113], v[142:145], v[186:189], v[110:113]
	v_mfma_f32_16x16x32_bf16 v[106:109], v[150:153], v[186:189], v[106:109]
	v_mfma_f32_16x16x32_bf16 v[98:101], v[142:145], v[194:197], v[98:101]
	v_mfma_f32_16x16x32_bf16 v[90:93], v[150:153], v[194:197], v[90:93]
	v_mfma_f32_16x16x32_bf16 v[86:89], v[142:145], v[202:205], v[86:89]
	v_mfma_f32_16x16x32_bf16 v[82:85], v[150:153], v[202:205], v[82:85]
	s_setprio 0
	s_barrier
	s_mov_b32 m0, s44
	v_lshl_add_u64 v[222:223], v[222:223], 0, s[6:7]
	ds_read_b128 v[206:209], v169
	ds_read_b128 v[210:213], v170
	ds_read_b128 v[214:217], v171
	ds_read_b128 v[218:221], v172
	global_load_lds_dwordx4 v[222:223], off
	v_lshl_add_u64 v[222:223], v[224:225], 0, s[6:7]
	s_mov_b32 m0, s45
	s_nop 0
	global_load_lds_dwordx4 v[222:223], off
	s_barrier
; #define PG8_STAGE(bufoff, gbase, voff) do { _Pragma("unroll") for (int _i = 0; _i < 2; ++_i) \
;         __builtin_amdgcn_global_load_lds((const unsigned*)((const char*)(gbase) + (voff)[_i]), (PG8_LAS unsigned*)(lds + (bufoff) + ldsw + _i * 8192), 16, 0, 0); } while (0)
; #define PG8_LDA(dst, b, h) do { _Pragma("unroll") for (int m = 0; m < 4; ++m) _Pragma("unroll") for (int k = 0; k < 2; ++k) dst[m][k] = *(const PG8_LAS bf16x8*)(lds + PG8_SA(b, h) + aoff + m * 2048 + k * 1024); } while (0)
; #define PG8_LDB(dst, b, h) do { _Pragma("unroll") for (int n = 0; n < 2; ++n) _Pragma("unroll") for (int k = 0; k < 2; ++k) dst[n][k] = *(const PG8_LAS bf16x8*)(lds + PG8_SB(b, h) + boff + n * 2048 + k * 1024); } while (0)
; #define PG8_MMA(ai, bj, At, Bt) do { __builtin_amdgcn_s_setprio(1); _Pragma("unroll") for (int m = 0; m < 4; ++m) _Pragma("unroll") for (int n = 0; n < 2; ++n) _Pragma("unroll") for (int k = 0; k < 2; ++k) \
;         acc[ai][bj][m][n] = __builtin_amdgcn_mfma_f32_16x16x32_bf16(Bt[n][k], At[m][k], acc[ai][bj][m][n], 0, 0, 0); __builtin_amdgcn_s_setprio(0); } while (0)
; #define PG8_WAIT_V(n) asm volatile("s_waitcnt vmcnt(" #n ")" ::: "memory")
; #define PG8_WAIT_L(n) asm volatile("s_waitcnt lgkmcnt(" #n ")" ::: "memory")
; #define PG8_BAR __builtin_amdgcn_s_barrier()
; #define PG8_SCHED __builtin_amdgcn_sched_barrier(0)
; template <class Epi, class Sched>
; __device__ __forceinline__ void gemm_phase(PG8_LAS unsigned char* lds, const Gemm g, const Sched& S, const Epi& E) {
;     ...
;             PG8_WAIT_V(6); PG8_BAR; PG8_MMA(1, 1, At, B1); PG8_BAR;
;             PG8_LDB(B0, 1, 0); PG8_SCHED; PG8_LDA(At, 1, 0); PG8_STAGE(PG8_SA(0, 1), a2 + hstep, voffA);
;             PG8_WAIT_L(8); PG8_BAR; PG8_WAIT_L(0); PG8_MMA(0, 0, At, B0); PG8_BAR; PG8_SCHED;
;             PG8_LDB(B1, 1, 1); PG8_STAGE(PG8_SB(1, 0), b3, voffB);
;             PG8_BAR; PG8_WAIT_L(0); PG8_MMA(0, 1, At, B1); PG8_BAR;
;             PG8_LDA(At, 1, 1); PG8_STAGE(PG8_SA(1, 0), a3, voffA);
;             PG8_BAR; PG8_WAIT_L(0); PG8_MMA(1, 0, At, B0); PG8_BAR; PG8_SCHED;
;             PG8_STAGE(PG8_SB(1, 1), b3 + hstep, voffB);
;             PG8_WAIT_V(6); PG8_BAR; PG8_MMA(1, 1, At, B1); PG8_BAR;
;         }
;         E(acc, cur, wr, wc, fr, fq);
	s_waitcnt lgkmcnt(0)
	s_setprio 1
	s_waitcnt lgkmcnt(0)
	v_mfma_f32_16x16x32_bf16 v[118:121], v[206:209], v[174:177], v[118:121]
	v_mfma_f32_16x16x32_bf16 v[114:117], v[214:217], v[174:177], v[114:117]
	v_mfma_f32_16x16x32_bf16 v[102:105], v[206:209], v[182:185], v[102:105]
	v_mfma_f32_16x16x32_bf16 v[94:97], v[214:217], v[182:185], v[94:97]
	v_mfma_f32_16x16x32_bf16 v[78:81], v[206:209], v[190:193], v[78:81]
	v_mfma_f32_16x16x32_bf16 v[74:77], v[214:217], v[190:193], v[74:77]
	v_mfma_f32_16x16x32_bf16 v[70:73], v[206:209], v[198:201], v[70:73]
	v_mfma_f32_16x16x32_bf16 v[66:69], v[214:217], v[198:201], v[66:69]
	v_mfma_f32_16x16x32_bf16 v[118:121], v[210:213], v[178:181], v[118:121]
	v_mfma_f32_16x16x32_bf16 v[114:117], v[218:221], v[178:181], v[114:117]
	v_mfma_f32_16x16x32_bf16 v[102:105], v[210:213], v[186:189], v[102:105]
	v_mfma_f32_16x16x32_bf16 v[94:97], v[218:221], v[186:189], v[94:97]
	v_mfma_f32_16x16x32_bf16 v[78:81], v[210:213], v[194:197], v[78:81]
	v_mfma_f32_16x16x32_bf16 v[74:77], v[218:221], v[194:197], v[74:77]
	v_mfma_f32_16x16x32_bf16 v[70:73], v[210:213], v[202:205], v[70:73]
	v_mfma_f32_16x16x32_bf16 v[66:69], v[218:221], v[202:205], v[66:69]
	s_setprio 0
	s_mov_b32 m0, s46
	v_lshl_add_u64 v[222:223], v[226:227], 0, s[6:7]
	s_barrier
	ds_read_b128 v[174:177], v155 offset:49152
	ds_read_b128 v[178:181], v155 offset:50176
	ds_read_b128 v[182:185], v155 offset:51200
	ds_read_b128 v[186:189], v155 offset:52224
	ds_read_b128 v[190:193], v155 offset:53248
	ds_read_b128 v[194:197], v155 offset:54272
	ds_read_b128 v[198:201], v155 offset:55296
	ds_read_b128 v[202:205], v155 offset:56320
	global_load_lds_dwordx4 v[222:223], off
	v_lshl_add_u64 v[222:223], v[228:229], 0, s[6:7]
	s_mov_b32 m0, s47
	s_nop 0
	global_load_lds_dwordx4 v[222:223], off
	s_barrier
	s_waitcnt lgkmcnt(0)
	s_setprio 1
	s_waitcnt lgkmcnt(0)
	v_mfma_f32_16x16x32_bf16 v[62:65], v[138:141], v[174:177], v[62:65]
	v_mfma_f32_16x16x32_bf16 v[58:61], v[146:149], v[174:177], v[58:61]
	v_mfma_f32_16x16x32_bf16 v[46:49], v[138:141], v[182:185], v[46:49]
	v_mfma_f32_16x16x32_bf16 v[42:45], v[146:149], v[182:185], v[42:45]
	v_mfma_f32_16x16x32_bf16 v[30:33], v[138:141], v[190:193], v[30:33]
	v_mfma_f32_16x16x32_bf16 v[26:29], v[146:149], v[190:193], v[26:29]
	v_mfma_f32_16x16x32_bf16 v[14:17], v[138:141], v[198:201], v[14:17]
	v_mfma_f32_16x16x32_bf16 v[10:13], v[146:149], v[198:201], v[10:13]
	v_mfma_f32_16x16x32_bf16 v[62:65], v[142:145], v[178:181], v[62:65]
	v_mfma_f32_16x16x32_bf16 v[58:61], v[150:153], v[178:181], v[58:61]
	v_mfma_f32_16x16x32_bf16 v[46:49], v[142:145], v[186:189], v[46:49]
	v_mfma_f32_16x16x32_bf16 v[42:45], v[150:153], v[186:189], v[42:45]
	v_mfma_f32_16x16x32_bf16 v[30:33], v[142:145], v[194:197], v[30:33]
	v_mfma_f32_16x16x32_bf16 v[26:29], v[150:153], v[194:197], v[26:29]
	v_mfma_f32_16x16x32_bf16 v[14:17], v[142:145], v[202:205], v[14:17]
	v_mfma_f32_16x16x32_bf16 v[10:13], v[150:153], v[202:205], v[10:13]
	s_setprio 0
	s_barrier
	s_add_u32 s28, s28, 0x20080
	s_addc_u32 s29, s29, 0
	s_mov_b32 m0, s48
	v_lshl_add_u64 v[138:139], s[28:29], 0, v[130:131]
	global_load_lds_dwordx4 v[138:139], off
	v_lshl_add_u64 v[138:139], s[28:29], 0, v[132:133]
	s_mov_b32 m0, s49
	s_nop 0
	global_load_lds_dwordx4 v[138:139], off
	s_waitcnt vmcnt(6)
	s_barrier
	s_setprio 1
	v_mfma_f32_16x16x32_bf16 v[54:57], v[206:209], v[174:177], v[54:57]
	v_mfma_f32_16x16x32_bf16 v[50:53], v[214:217], v[174:177], v[50:53]
	v_mfma_f32_16x16x32_bf16 v[38:41], v[206:209], v[182:185], v[38:41]
	v_mfma_f32_16x16x32_bf16 v[34:37], v[214:217], v[182:185], v[34:37]
	v_mfma_f32_16x16x32_bf16 v[22:25], v[206:209], v[190:193], v[22:25]
	v_mfma_f32_16x16x32_bf16 v[18:21], v[214:217], v[190:193], v[18:21]
	v_mfma_f32_16x16x32_bf16 v[6:9], v[206:209], v[198:201], v[6:9]
	v_mfma_f32_16x16x32_bf16 v[2:5], v[214:217], v[198:201], v[2:5]
	v_mfma_f32_16x16x32_bf16 v[54:57], v[210:213], v[178:181], v[54:57]
	v_mfma_f32_16x16x32_bf16 v[50:53], v[218:221], v[178:181], v[50:53]
	v_mfma_f32_16x16x32_bf16 v[38:41], v[210:213], v[186:189], v[38:41]
	v_mfma_f32_16x16x32_bf16 v[34:37], v[218:221], v[186:189], v[34:37]
	v_mfma_f32_16x16x32_bf16 v[22:25], v[210:213], v[194:197], v[22:25]
	v_mfma_f32_16x16x32_bf16 v[18:21], v[218:221], v[194:197], v[18:21]
	v_mfma_f32_16x16x32_bf16 v[6:9], v[210:213], v[202:205], v[6:9]
	v_mfma_f32_16x16x32_bf16 v[2:5], v[218:221], v[202:205], v[2:5]
	s_setprio 0
	s_add_i32 s61, s61, 2
	s_add_u32 s26, s26, 0x100
	s_addc_u32 s27, s27, 0
	s_add_u32 s59, s59, 0x100
	s_addc_u32 s60, s60, 0
	s_cmp_gt_u32 s61, 5
	s_barrier
	s_cbranch_scc0 .LBB0_713
	s_cmp_eq_u32 s0, 16
	s_cbranch_scc0 .Lp4r_go
	s_cmp_eq_u32 s50, 2
	s_cbranch_scc0 .Lp4r_go
	s_and_b32 vcc_hi, s94, 7
	s_lshl_b32 vcc_hi, vcc_hi, 8
	s_add_i32 vcc_hi, vcc_hi, 0xb23400
	v_mov_b32_e32 v138, vcc_hi
	v_mov_b32_e32 v139, 0
	s_movk_i32 vcc_lo, 0x2000
	s_mov_b64 exec, 1
